# RES1 epilogue (layers 1-2): the eight row-stat loads are issued together and waited once instead of one full-latency wait per load
# speedup vs baseline: 1.1064x; 1.0011x over previous
;     ...
;       const int b = m0e / TALL, t0 = m0e - b * TALL;
;       const bool isctx = t0 < CTX;
;       float* xb = isctx ? P.zctx + ((size_t)(b * CTX + t0)) * D : P.out + ((size_t)(b * SEQ + t0 - CTX)) * D;
;       const float* g = P.mod + ((size_t)(l * 17 + (isctx ? 16 : b))) * 6144 + (EPI == EPI_RES1 ? 2 * D : 5 * D);
;       const float* xs = (EPI == EPI_RES1 && l == 0) ? (isctx ? P.ctx + ((size_t)(b * CTX + t0)) * D : P.x + ((size_t)(b * SEQ + t0 - CTX)) * D) : xb;
;       const float gv0 = g[n0e + cb], gv1 = g[n0e + cb + 32];
;       const bool haveln = !(EPI == EPI_RES1 && l == 0);
;       const float* lgp = (EPI == EPI_RES1) ? P.post2_g + (size_t)(l > 0 ? l - 1 : 0) * D : P.post1_g + (size_t)l * D;
;       const float* lbp = (EPI == EPI_RES1) ? P.post2_b + (size_t)(l > 0 ? l - 1 : 0) * D : P.post1_b + (size_t)l * D;
;       const float lg0 = lgp[n0e + cb], lg1 = lgp[n0e + cb + 32], lb0 = lbp[n0e + cb], lb1 = lbp[n0e + cb + 32];
; #pragma unroll
;       for (int mi = 0; mi < 2; ++mi) {
;         float xo[2][16];
;         float2 ms[16];
; #pragma unroll
;         for (int ni = 0; ni < 2; ++ni)
; #pragma unroll
;           for (int i = 0; i < 16; ++i)
;             xo[ni][i] = xs[(size_t)(rb + mi * 32 + (i & 3) + 8 * (i >> 2)) * D + n0e + cb + ni * 32];
.LBB0_244:
	v_readlane_b32 s18, v251, 50
	v_readlane_b32 s19, v251, 51
	s_mul_i32 s1, s18, 17
	s_add_i32 s1, s16, s1
	v_readlane_b32 s16, v253, 20
	s_mul_hi_i32 s15, s1, 0x6000
	s_mulk_i32 s1, 0x6000
	v_readlane_b32 s20, v253, 24
	v_add_u32_e32 v64, s0, v72
	v_readlane_b32 s17, v253, 21
	v_readlane_b32 s21, v253, 25
	s_add_u32 s16, s20, s1
	v_ashrrev_i32_e32 v65, 31, v64
	s_addc_u32 s17, s21, s15
	v_lshlrev_b64 v[70:71], 2, v[64:65]
	v_lshl_add_u64 v[64:65], s[16:17], 0, v[70:71]
	s_mov_b64 s[16:17], 0x2000
	s_movk_i32 s1, 0x2000
	v_lshl_add_u64 v[68:69], v[64:65], 0, s[16:17]
	v_add_co_u32_e32 v64, vcc, s1, v64
	s_ashr_i32 s1, s0, 31
	s_lshl_b64 s[86:87], s[0:1], 2
	v_addc_co_u32_e32 v65, vcc, 0, v65, vcc
	v_lshl_add_u64 v[74:75], s[10:11], 0, v[70:71]
	s_add_u32 s0, s34, s86
	global_load_dword v67, v[64:65], off
	s_nop 0
	global_load_dword v65, v[68:69], off offset:128
	s_nop 0
	global_load_dword v68, v[74:75], off
	global_load_dword v64, v[74:75], off offset:128
	v_lshl_add_u64 v[74:75], s[12:13], 0, v[70:71]
	v_ashrrev_i32_e32 v73, 31, v72
	s_addc_u32 s1, s35, s87
	v_ashrrev_i32_e32 v79, 31, v78
	global_load_dword v70, v[74:75], off
	global_load_dword v66, v[74:75], off offset:128
	v_lshl_add_u64 v[74:75], v[72:73], 2, s[0:1]
	v_lshlrev_b64 v[76:77], 12, v[78:79]
	s_mov_b64 s[0:1], 0x1000
	v_lshl_add_u64 v[124:125], v[76:77], 0, s[0:1]
	s_mov_b64 s[0:1], 0x3000
	v_lshl_add_u64 v[120:121], v[76:77], 0, s[0:1]
	s_mov_b64 s[0:1], 0x8000
	v_lshl_add_u64 v[118:119], v[76:77], 0, s[0:1]
	s_mov_b64 s[0:1], 0x9000
	v_lshl_add_u64 v[116:117], v[76:77], 0, s[0:1]
	s_mov_b64 s[0:1], 0xa000
	v_lshl_add_u64 v[114:115], v[76:77], 0, s[0:1]
	s_mov_b64 s[0:1], 0xb000
	v_lshl_add_u64 v[112:113], v[76:77], 0, s[0:1]
	s_mov_b64 s[0:1], 0x10000
	v_lshl_add_u64 v[110:111], v[76:77], 0, s[0:1]
	s_mov_b64 s[0:1], 0x11000
	v_lshl_add_u64 v[108:109], v[76:77], 0, s[0:1]
	s_mov_b64 s[0:1], 0x12000
	v_lshl_add_u64 v[104:105], v[76:77], 0, s[0:1]
	s_mov_b64 s[0:1], 0x13000
	v_lshl_add_u64 v[102:103], v[76:77], 0, s[0:1]
	s_mov_b64 s[0:1], 0x18000
	v_lshl_add_u64 v[100:101], v[76:77], 0, s[0:1]
	s_mov_b64 s[0:1], 0x19000
	v_lshl_add_u64 v[98:99], v[76:77], 0, s[0:1]
	s_mov_b64 s[0:1], 0x1a000
	v_lshl_add_u64 v[122:123], v[76:77], 0, s[16:17]
	v_lshl_add_u64 v[94:95], v[76:77], 0, s[0:1]
	s_mov_b64 s[0:1], 0x1b000
	v_lshl_add_u64 v[80:81], v[74:75], 0, v[76:77]
	v_lshl_add_u64 v[82:83], v[74:75], 0, v[124:125]
	v_lshl_add_u64 v[84:85], v[74:75], 0, v[122:123]
	v_lshl_add_u64 v[86:87], v[74:75], 0, v[120:121]
	v_lshl_add_u64 v[88:89], v[74:75], 0, v[118:119]
	v_lshl_add_u64 v[92:93], v[74:75], 0, v[116:117]
	v_lshl_add_u64 v[126:127], v[74:75], 0, v[114:115]
	v_lshl_add_u64 v[128:129], v[74:75], 0, v[112:113]
	v_lshl_add_u64 v[148:149], v[74:75], 0, v[110:111]
	v_lshl_add_u64 v[90:91], v[76:77], 0, s[0:1]
	v_lshl_add_u64 v[152:153], v[74:75], 0, v[108:109]
	v_lshl_add_u64 v[156:157], v[74:75], 0, v[104:105]
	v_lshl_add_u64 v[158:159], v[74:75], 0, v[102:103]
	v_lshl_add_u64 v[160:161], v[74:75], 0, v[100:101]
	v_lshl_add_u64 v[164:165], v[74:75], 0, v[98:99]
	v_lshl_add_u64 v[166:167], v[74:75], 0, v[94:95]
	v_lshl_add_u64 v[168:169], v[74:75], 0, v[90:91]
	global_load_dword v151, v[80:81], off
	global_load_dword v150, v[82:83], off
	global_load_dword v145, v[84:85], off
	global_load_dword v144, v[86:87], off
	s_nop 0
	global_load_dword v86, v[86:87], off offset:128
	s_nop 0
	global_load_dword v87, v[84:85], off offset:128
	global_load_dword v106, v[82:83], off offset:128
	global_load_dword v107, v[80:81], off offset:128
	global_load_dword v147, v[88:89], off
	global_load_dword v146, v[92:93], off
	global_load_dword v143, v[126:127], off
	global_load_dword v142, v[128:129], off
	global_load_dword v82, v[128:129], off offset:128
	global_load_dword v83, v[126:127], off offset:128
	s_nop 0
	global_load_dword v92, v[92:93], off offset:128
	s_nop 0
	global_load_dword v93, v[88:89], off offset:128
	global_load_dword v141, v[148:149], off
	global_load_dword v140, v[152:153], off
	global_load_dword v139, v[156:157], off
	global_load_dword v138, v[158:159], off
	global_load_dword v80, v[158:159], off offset:128
	global_load_dword v81, v[156:157], off offset:128
	global_load_dword v88, v[152:153], off offset:128
	global_load_dword v89, v[148:149], off offset:128
	global_load_dword v129, v[160:161], off
	global_load_dword v128, v[164:165], off
	global_load_dword v127, v[166:167], off
	global_load_dword v126, v[168:169], off
	s_nop 0
	global_load_dword v148, v[168:169], off offset:128
	global_load_dword v149, v[166:167], off offset:128
	global_load_dword v84, v[164:165], off offset:128
	global_load_dword v85, v[160:161], off offset:128
	v_add_u32_e32 v78, s14, v78
	v_cndmask_b32_e64 v69, 0, 1, s[6:7]
	v_cmp_ne_u32_e64 s[0:1], 1, v69
	s_andn2_b64 vcc, exec, s[6:7]
	v_ashrrev_i32_e32 v79, 31, v78
	v_readlane_b32 s18, v253, 22
	v_readlane_b32 s19, v253, 23
	v_readlane_b32 s22, v253, 26
	v_readlane_b32 s23, v253, 27
	v_readlane_b32 s24, v253, 28
	v_readlane_b32 s25, v253, 29
	v_readlane_b32 s26, v253, 30
	v_readlane_b32 s27, v253, 31
	v_readlane_b32 s28, v253, 32
	v_readlane_b32 s29, v253, 33
	v_readlane_b32 s30, v253, 34
	v_readlane_b32 s31, v253, 35
	s_cbranch_vccnz .LBB0_246
;     ...
; #pragma unroll
;         for (int i = 0; i < 16; ++i)
;           ms[i] = haveln ? *(const float2*)(P.stats + (size_t)(m0e + rb + mi * 32 + (i & 3) + 8 * (i >> 2)) * 2) : make_float2(0.f, 1.f);
;         if (haveln) {
; #pragma unroll
;           for (int ni = 0; ni < 2; ++ni)
; #pragma unroll
;             for (int i = 0; i < 16; ++i) xo[ni][i] = (xo[ni][i] - ms[i].x) * ms[i].y * (ni ? lg1 : lg0) + (ni ? lb1 : lb0);
;         }
	v_readlane_b32 s14, v252, 6
	v_readlane_b32 s15, v252, 7
	s_nop 1
	v_lshl_add_u64 v[152:153], v[78:79], 3, s[14:15]
	global_load_dwordx4 v[156:159], v[152:153], off
	global_load_dwordx4 v[172:175], v[152:153], off offset:16
	global_load_dwordx4 v[176:179], v[152:153], off offset:64
	global_load_dwordx4 v[180:183], v[152:153], off offset:80
	global_load_dwordx4 v[184:187], v[152:153], off offset:128
	global_load_dwordx4 v[188:191], v[152:153], off offset:144
	global_load_dwordx4 v[192:195], v[152:153], off offset:192
	global_load_dwordx4 v[196:199], v[152:153], off offset:208
	s_waitcnt vmcnt(0)
	v_mov_b32_e32 v160, v158
	v_mov_b32_e32 v161, v156
	v_pk_add_f32 v[150:151], v[150:151], v[160:161] neg_lo:[0,1] neg_hi:[0,1]
	v_mov_b32_e32 v156, v159
	v_pk_add_f32 v[106:107], v[106:107], v[160:161] neg_lo:[0,1] neg_hi:[0,1]
	v_pk_mul_f32 v[150:151], v[150:151], v[156:157]
	v_pk_mul_f32 v[106:107], v[106:107], v[156:157]
	v_pk_fma_f32 v[150:151], v[68:69], v[150:151], v[70:71] op_sel_hi:[0,1,0]
	v_pk_fma_f32 v[106:107], v[64:65], v[106:107], v[66:67] op_sel_hi:[0,1,0]
	v_mov_b32_e32 v160, v174
	v_mov_b32_e32 v161, v172
	v_pk_add_f32 v[144:145], v[144:145], v[160:161] neg_lo:[0,1] neg_hi:[0,1]
	v_mov_b32_e32 v172, v175
	v_pk_add_f32 v[86:87], v[86:87], v[160:161] neg_lo:[0,1] neg_hi:[0,1]
	v_pk_mul_f32 v[144:145], v[144:145], v[172:173]
	v_pk_mul_f32 v[86:87], v[86:87], v[172:173]
	v_pk_fma_f32 v[144:145], v[68:69], v[144:145], v[70:71] op_sel_hi:[0,1,0]
	v_pk_fma_f32 v[86:87], v[64:65], v[86:87], v[66:67] op_sel_hi:[0,1,0]
	v_mov_b32_e32 v160, v178
	v_mov_b32_e32 v161, v176
	v_pk_add_f32 v[146:147], v[146:147], v[160:161] neg_lo:[0,1] neg_hi:[0,1]
	v_mov_b32_e32 v176, v179
	v_pk_add_f32 v[92:93], v[92:93], v[160:161] neg_lo:[0,1] neg_hi:[0,1]
	v_pk_mul_f32 v[146:147], v[146:147], v[176:177]
	v_pk_mul_f32 v[92:93], v[92:93], v[176:177]
	v_pk_fma_f32 v[146:147], v[68:69], v[146:147], v[70:71] op_sel_hi:[0,1,0]
	v_pk_fma_f32 v[92:93], v[64:65], v[92:93], v[66:67] op_sel_hi:[0,1,0]
	v_mov_b32_e32 v160, v182
	v_mov_b32_e32 v161, v180
	v_pk_add_f32 v[142:143], v[142:143], v[160:161] neg_lo:[0,1] neg_hi:[0,1]
	v_mov_b32_e32 v180, v183
	v_pk_add_f32 v[82:83], v[82:83], v[160:161] neg_lo:[0,1] neg_hi:[0,1]
	v_pk_mul_f32 v[142:143], v[142:143], v[180:181]
	v_pk_mul_f32 v[82:83], v[82:83], v[180:181]
	v_pk_fma_f32 v[142:143], v[68:69], v[142:143], v[70:71] op_sel_hi:[0,1,0]
	v_pk_fma_f32 v[82:83], v[64:65], v[82:83], v[66:67] op_sel_hi:[0,1,0]
	v_mov_b32_e32 v160, v186
	v_mov_b32_e32 v161, v184
	v_pk_add_f32 v[140:141], v[140:141], v[160:161] neg_lo:[0,1] neg_hi:[0,1]
	v_mov_b32_e32 v184, v187
	v_pk_add_f32 v[88:89], v[88:89], v[160:161] neg_lo:[0,1] neg_hi:[0,1]
	v_pk_mul_f32 v[140:141], v[140:141], v[184:185]
	v_pk_mul_f32 v[88:89], v[88:89], v[184:185]
	v_pk_fma_f32 v[140:141], v[68:69], v[140:141], v[70:71] op_sel_hi:[0,1,0]
	v_pk_fma_f32 v[88:89], v[64:65], v[88:89], v[66:67] op_sel_hi:[0,1,0]
	v_mov_b32_e32 v160, v190
	v_mov_b32_e32 v161, v188
	v_pk_add_f32 v[138:139], v[138:139], v[160:161] neg_lo:[0,1] neg_hi:[0,1]
	v_mov_b32_e32 v188, v191
	v_pk_add_f32 v[80:81], v[80:81], v[160:161] neg_lo:[0,1] neg_hi:[0,1]
	v_pk_mul_f32 v[138:139], v[138:139], v[188:189]
	v_pk_mul_f32 v[80:81], v[80:81], v[188:189]
	v_pk_fma_f32 v[138:139], v[68:69], v[138:139], v[70:71] op_sel_hi:[0,1,0]
	v_pk_fma_f32 v[80:81], v[64:65], v[80:81], v[66:67] op_sel_hi:[0,1,0]
	v_mov_b32_e32 v160, v194
	v_mov_b32_e32 v161, v192
	v_pk_add_f32 v[128:129], v[128:129], v[160:161] neg_lo:[0,1] neg_hi:[0,1]
	v_mov_b32_e32 v192, v195
	v_pk_add_f32 v[84:85], v[84:85], v[160:161] neg_lo:[0,1] neg_hi:[0,1]
	v_pk_mul_f32 v[128:129], v[128:129], v[192:193]
	v_pk_mul_f32 v[84:85], v[84:85], v[192:193]
	v_pk_fma_f32 v[128:129], v[68:69], v[128:129], v[70:71] op_sel_hi:[0,1,0]
	v_pk_fma_f32 v[84:85], v[64:65], v[84:85], v[66:67] op_sel_hi:[0,1,0]
	v_mov_b32_e32 v152, v198
	v_mov_b32_e32 v153, v196
	v_pk_add_f32 v[126:127], v[126:127], v[152:153] neg_lo:[0,1] neg_hi:[0,1]
	v_mov_b32_e32 v196, v199
	v_pk_add_f32 v[148:149], v[148:149], v[152:153] neg_lo:[0,1] neg_hi:[0,1]
	v_pk_mul_f32 v[126:127], v[126:127], v[196:197]
	v_pk_mul_f32 v[148:149], v[148:149], v[196:197]
	v_pk_fma_f32 v[126:127], v[68:69], v[126:127], v[70:71] op_sel_hi:[0,1,0]
	v_pk_fma_f32 v[148:149], v[64:65], v[148:149], v[66:67] op_sel_hi:[0,1,0]
;     ...
; #pragma unroll
;         for (int ni = 0; ni < 2; ++ni)
; #pragma unroll
;           for (int i = 0; i < 16; ++i) {
;             float* px = xb + (size_t)(rb + mi * 32 + (i & 3) + 8 * (i >> 2)) * D + n0e + cb + ni * 32;
;             if (dummy == 3) { if (acc[mi][ni][i] == 12345.678f) *px = 0.f; }
;             else {
;               float xn = ALPHA * xo[ni][i] + (ni ? gv1 : gv0) * acc[mi][ni][i];
;               if (dummy) { asm volatile("" :: "v"(xn)); xn = xo[ni][i]; }
;               *px = xn;
;             }
;           }
.LBB0_246:
	s_add_u32 s2, s2, s86
	s_addc_u32 s3, s3, s87
	v_lshl_add_u64 v[72:73], v[72:73], 2, s[2:3]
	s_waitcnt vmcnt(31)
	v_mul_f32_e32 v69, 0x3fd744fd, v151
	v_lshl_add_u64 v[152:153], v[72:73], 0, v[76:77]
	v_fmac_f32_e32 v69, v48, v67
	s_waitcnt vmcnt(30)
	v_mul_f32_e32 v48, 0x3fd744fd, v150
	global_store_dword v[152:153], v69, off
	v_lshl_add_u64 v[124:125], v[72:73], 0, v[124:125]
	v_fmac_f32_e32 v48, v49, v67
	s_waitcnt vmcnt(30)
	v_mul_f32_e32 v69, 0x3fd744fd, v145
	global_store_dword v[124:125], v48, off
	v_lshl_add_u64 v[48:49], v[72:73], 0, v[122:123]
	v_fmac_f32_e32 v69, v50, v67
	s_waitcnt vmcnt(30)
	v_mul_f32_e32 v50, 0x3fd744fd, v144
	global_store_dword v[48:49], v69, off
	v_lshl_add_u64 v[120:121], v[72:73], 0, v[120:121]
	v_fmac_f32_e32 v50, v51, v67
	s_waitcnt vmcnt(26)
	v_mul_f32_e32 v69, 0x3fd744fd, v147
	global_store_dword v[120:121], v50, off
	v_lshl_add_u64 v[50:51], v[72:73], 0, v[118:119]
	v_fmac_f32_e32 v69, v52, v67
	s_waitcnt vmcnt(26)
	v_mul_f32_e32 v52, 0x3fd744fd, v146
	global_store_dword v[50:51], v69, off
	v_lshl_add_u64 v[116:117], v[72:73], 0, v[116:117]
	v_fmac_f32_e32 v52, v53, v67
	s_waitcnt vmcnt(26)
	v_mul_f32_e32 v69, 0x3fd744fd, v143
	global_store_dword v[116:117], v52, off
	v_lshl_add_u64 v[52:53], v[72:73], 0, v[114:115]
	v_fmac_f32_e32 v69, v54, v67
	s_waitcnt vmcnt(26)
	v_mul_f32_e32 v54, 0x3fd744fd, v142
	global_store_dword v[52:53], v69, off
	v_lshl_add_u64 v[112:113], v[72:73], 0, v[112:113]
	v_fmac_f32_e32 v54, v55, v67
	s_waitcnt vmcnt(22)
	v_mul_f32_e32 v69, 0x3fd744fd, v141
	global_store_dword v[112:113], v54, off
	v_lshl_add_u64 v[54:55], v[72:73], 0, v[110:111]
	v_fmac_f32_e32 v69, v56, v67
	s_waitcnt vmcnt(22)
	v_mul_f32_e32 v56, 0x3fd744fd, v140
	global_store_dword v[54:55], v69, off
	v_lshl_add_u64 v[108:109], v[72:73], 0, v[108:109]
	v_fmac_f32_e32 v56, v57, v67
	s_waitcnt vmcnt(22)
	v_mul_f32_e32 v69, 0x3fd744fd, v139
	global_store_dword v[108:109], v56, off
	v_lshl_add_u64 v[56:57], v[72:73], 0, v[104:105]
	v_fmac_f32_e32 v69, v58, v67
	s_waitcnt vmcnt(22)
	v_mul_f32_e32 v58, 0x3fd744fd, v138
	global_store_dword v[56:57], v69, off
	v_lshl_add_u64 v[102:103], v[72:73], 0, v[102:103]
	v_fmac_f32_e32 v58, v59, v67
	s_waitcnt vmcnt(18)
	v_mul_f32_e32 v69, 0x3fd744fd, v129
	global_store_dword v[102:103], v58, off
	v_lshl_add_u64 v[58:59], v[72:73], 0, v[100:101]
	v_fmac_f32_e32 v69, v60, v67
	global_store_dword v[58:59], v69, off
	s_waitcnt vmcnt(18)
	v_mul_f32_e32 v69, 0x3fd744fd, v127
	v_fmac_f32_e32 v69, v62, v67
	s_waitcnt vmcnt(17)
	v_mul_f32_e32 v62, 0x3fd744fd, v126
	v_lshl_add_u64 v[90:91], v[72:73], 0, v[90:91]
	v_fmac_f32_e32 v62, v63, v67
	global_store_dword v[90:91], v62, off
	v_mul_f32_e32 v62, 0x3fd744fd, v107
	v_fmac_f32_e32 v62, v32, v65
	v_mul_f32_e32 v32, 0x3fd744fd, v106
	v_fmac_f32_e32 v32, v33, v65
	global_store_dword v[124:125], v32, off offset:128
	v_mul_f32_e32 v32, 0x3fd744fd, v87
	v_fmac_f32_e32 v32, v34, v65
	global_store_dword v[48:49], v32, off offset:128
	v_mul_f32_e32 v32, 0x3fd744fd, v86
	v_fmac_f32_e32 v32, v35, v65
	global_store_dword v[120:121], v32, off offset:128
	v_mul_f32_e32 v32, 0x3fd744fd, v93
	v_fmac_f32_e32 v32, v36, v65
	global_store_dword v[50:51], v32, off offset:128
	v_mul_f32_e32 v32, 0x3fd744fd, v92
	v_fmac_f32_e32 v32, v37, v65
	global_store_dword v[116:117], v32, off offset:128
	v_mul_f32_e32 v32, 0x3fd744fd, v83
	v_fmac_f32_e32 v32, v38, v65
	global_store_dword v[52:53], v32, off offset:128
	v_mul_f32_e32 v32, 0x3fd744fd, v82
	v_fmac_f32_e32 v32, v39, v65
	global_store_dword v[112:113], v32, off offset:128
	v_mul_f32_e32 v32, 0x3fd744fd, v89
	v_fmac_f32_e32 v32, v40, v65
	global_store_dword v[54:55], v32, off offset:128
	v_mul_f32_e32 v32, 0x3fd744fd, v88
	v_fmac_f32_e32 v32, v41, v65
	global_store_dword v[108:109], v32, off offset:128
	v_mul_f32_e32 v32, 0x3fd744fd, v81
	v_fmac_f32_e32 v32, v42, v65
	global_store_dword v[56:57], v32, off offset:128
	v_mul_f32_e32 v32, 0x3fd744fd, v80
	v_fmac_f32_e32 v32, v43, v65
	global_store_dword v[102:103], v32, off offset:128
	s_waitcnt vmcnt(25)
	v_mul_f32_e32 v32, 0x3fd744fd, v85
	v_fmac_f32_e32 v32, v44, v65
	global_store_dword v[58:59], v32, off offset:128
	v_mul_f32_e32 v32, 0x3fd744fd, v84
	v_lshl_add_u64 v[98:99], v[72:73], 0, v[98:99]
	v_mul_f32_e32 v60, 0x3fd744fd, v128
	v_fmac_f32_e32 v32, v45, v65
	v_fmac_f32_e32 v60, v61, v67
	global_store_dword v[98:99], v32, off offset:128
	v_mul_f32_e32 v32, 0x3fd744fd, v149
	global_store_dword v[98:99], v60, off
	v_lshl_add_u64 v[60:61], v[72:73], 0, v[94:95]
	v_fmac_f32_e32 v32, v46, v65
	global_store_dword v[60:61], v32, off offset:128
	v_mul_f32_e32 v32, 0x3fd744fd, v148
	s_mov_b64 s[2:3], 0x20000
	v_fmac_f32_e32 v32, v47, v65
	v_lshl_add_u64 v[92:93], v[76:77], 0, s[2:3]
	s_mov_b64 s[2:3], 0x21000
	global_store_dword v[90:91], v32, off offset:128
	v_lshl_add_u64 v[90:91], v[76:77], 0, s[2:3]
	s_mov_b64 s[2:3], 0x22000
	v_lshl_add_u64 v[88:89], v[76:77], 0, s[2:3]
	s_mov_b64 s[2:3], 0x23000
	v_lshl_add_u64 v[86:87], v[76:77], 0, s[2:3]
	s_mov_b64 s[2:3], 0x28000
	v_lshl_add_u64 v[84:85], v[76:77], 0, s[2:3]
	s_mov_b64 s[2:3], 0x29000
	v_lshl_add_u64 v[82:83], v[76:77], 0, s[2:3]
	s_mov_b64 s[2:3], 0x2a000
	v_lshl_add_u64 v[80:81], v[76:77], 0, s[2:3]
	s_mov_b64 s[2:3], 0x2b000
	global_store_dword v[152:153], v62, off offset:128
	v_lshl_add_u64 v[62:63], v[76:77], 0, s[2:3]
	s_mov_b64 s[2:3], 0x30000
	global_store_dword v[60:61], v69, off
	v_lshl_add_u64 v[60:61], v[76:77], 0, s[2:3]
	s_mov_b64 s[2:3], 0x31000
	v_lshl_add_u64 v[58:59], v[76:77], 0, s[2:3]
	s_mov_b64 s[2:3], 0x32000
	v_lshl_add_u64 v[54:55], v[76:77], 0, s[2:3]
;     ...
; #pragma unroll
;         for (int ni = 0; ni < 2; ++ni)
; #pragma unroll
;           for (int i = 0; i < 16; ++i)
;             xo[ni][i] = xs[(size_t)(rb + mi * 32 + (i & 3) + 8 * (i >> 2)) * D + n0e + cb + ni * 32];
; #pragma unroll
;         for (int i = 0; i < 16; ++i)
;           ms[i] = haveln ? *(const float2*)(P.stats + (size_t)(m0e + rb + mi * 32 + (i & 3) + 8 * (i >> 2)) * 2) : make_float2(0.f, 1.f);
;         if (haveln) {
; #pragma unroll
;           for (int ni = 0; ni < 2; ++ni)
; #pragma unroll
;             for (int i = 0; i < 16; ++i) xo[ni][i] = (xo[ni][i] - ms[i].x) * ms[i].y * (ni ? lg1 : lg0) + (ni ? lb1 : lb0);
;         }
	s_mov_b64 s[2:3], 0x33000
	v_lshl_add_u64 v[52:53], v[76:77], 0, s[2:3]
	s_mov_b64 s[2:3], 0x38000
	v_lshl_add_u64 v[50:51], v[76:77], 0, s[2:3]
	s_mov_b64 s[2:3], 0x39000
	v_lshl_add_u64 v[48:49], v[76:77], 0, s[2:3]
	s_mov_b64 s[2:3], 0x3a000
	v_lshl_add_u64 v[46:47], v[76:77], 0, s[2:3]
	s_mov_b64 s[2:3], 0x3b000
	v_lshl_add_u64 v[32:33], v[74:75], 0, v[92:93]
	v_lshl_add_u64 v[34:35], v[74:75], 0, v[90:91]
	v_lshl_add_u64 v[36:37], v[74:75], 0, v[88:89]
	v_lshl_add_u64 v[38:39], v[74:75], 0, v[86:87]
	v_lshl_add_u64 v[40:41], v[74:75], 0, v[84:85]
	v_lshl_add_u64 v[44:45], v[74:75], 0, v[82:83]
	v_lshl_add_u64 v[94:95], v[74:75], 0, v[80:81]
	v_lshl_add_u64 v[98:99], v[74:75], 0, v[62:63]
	v_lshl_add_u64 v[106:107], v[74:75], 0, v[60:61]
	v_lshl_add_u64 v[42:43], v[76:77], 0, s[2:3]
	v_lshl_add_u64 v[110:111], v[74:75], 0, v[58:59]
	v_lshl_add_u64 v[112:113], v[74:75], 0, v[54:55]
	v_lshl_add_u64 v[114:115], v[74:75], 0, v[52:53]
	v_lshl_add_u64 v[116:117], v[74:75], 0, v[50:51]
	v_lshl_add_u64 v[118:119], v[74:75], 0, v[48:49]
	v_lshl_add_u64 v[120:121], v[74:75], 0, v[46:47]
	v_lshl_add_u64 v[122:123], v[74:75], 0, v[42:43]
	global_load_dword v109, v[32:33], off
	global_load_dword v108, v[34:35], off
	global_load_dword v103, v[36:37], off
	global_load_dword v102, v[38:39], off
	s_nop 0
	global_load_dword v38, v[38:39], off offset:128
	s_nop 0
	global_load_dword v39, v[36:37], off offset:128
	global_load_dword v56, v[34:35], off offset:128
	global_load_dword v57, v[32:33], off offset:128
	global_load_dword v105, v[40:41], off
	global_load_dword v104, v[44:45], off
	global_load_dword v101, v[94:95], off
	global_load_dword v100, v[98:99], off
	global_load_dword v34, v[98:99], off offset:128
	global_load_dword v35, v[94:95], off offset:128
	s_nop 0
	global_load_dword v44, v[44:45], off offset:128
	s_nop 0
	global_load_dword v45, v[40:41], off offset:128
	global_load_dword v99, v[106:107], off
	global_load_dword v98, v[110:111], off
	global_load_dword v95, v[112:113], off
	global_load_dword v94, v[114:115], off
	global_load_dword v32, v[114:115], off offset:128
	global_load_dword v33, v[112:113], off offset:128
	global_load_dword v40, v[110:111], off offset:128
	global_load_dword v41, v[106:107], off offset:128
	global_load_dword v77, v[116:117], off
	global_load_dword v76, v[118:119], off
	global_load_dword v75, v[120:121], off
	global_load_dword v74, v[122:123], off
	s_nop 0
	global_load_dword v106, v[122:123], off offset:128
	global_load_dword v107, v[120:121], off offset:128
	global_load_dword v36, v[118:119], off offset:128
	global_load_dword v37, v[116:117], off offset:128
	s_and_b64 vcc, exec, s[0:1]
	s_cbranch_vccnz .LBB0_230
	v_readlane_b32 s0, v252, 6
	v_readlane_b32 s1, v252, 7
	s_nop 1
	v_lshl_add_u64 v[78:79], v[78:79], 3, s[0:1]
	global_load_dwordx4 v[110:113], v[78:79], off offset:256
	global_load_dwordx4 v[172:175], v[78:79], off offset:272
	global_load_dwordx4 v[176:179], v[78:79], off offset:320
	global_load_dwordx4 v[180:183], v[78:79], off offset:336
	global_load_dwordx4 v[184:187], v[78:79], off offset:384
	global_load_dwordx4 v[188:191], v[78:79], off offset:400
	global_load_dwordx4 v[192:195], v[78:79], off offset:448
	global_load_dwordx4 v[196:199], v[78:79], off offset:464
	s_waitcnt vmcnt(0)
	v_mov_b32_e32 v114, v112
	v_mov_b32_e32 v115, v110
	v_pk_add_f32 v[108:109], v[108:109], v[114:115] neg_lo:[0,1] neg_hi:[0,1]
	v_mov_b32_e32 v110, v113
	v_pk_add_f32 v[56:57], v[56:57], v[114:115] neg_lo:[0,1] neg_hi:[0,1]
	v_pk_mul_f32 v[108:109], v[108:109], v[110:111]
	v_pk_mul_f32 v[56:57], v[56:57], v[110:111]
	v_pk_fma_f32 v[108:109], v[68:69], v[108:109], v[70:71] op_sel_hi:[0,1,0]
	v_pk_fma_f32 v[56:57], v[64:65], v[56:57], v[66:67] op_sel_hi:[0,1,0]
	v_mov_b32_e32 v114, v174
	v_mov_b32_e32 v115, v172
	v_pk_add_f32 v[102:103], v[102:103], v[114:115] neg_lo:[0,1] neg_hi:[0,1]
	v_mov_b32_e32 v172, v175
	v_pk_add_f32 v[38:39], v[38:39], v[114:115] neg_lo:[0,1] neg_hi:[0,1]
	v_pk_mul_f32 v[102:103], v[102:103], v[172:173]
	v_pk_mul_f32 v[38:39], v[38:39], v[172:173]
	v_pk_fma_f32 v[102:103], v[68:69], v[102:103], v[70:71] op_sel_hi:[0,1,0]
	v_pk_fma_f32 v[38:39], v[64:65], v[38:39], v[66:67] op_sel_hi:[0,1,0]
	v_mov_b32_e32 v114, v178
	v_mov_b32_e32 v115, v176
	v_pk_add_f32 v[104:105], v[104:105], v[114:115] neg_lo:[0,1] neg_hi:[0,1]
	v_mov_b32_e32 v176, v179
	v_pk_add_f32 v[44:45], v[44:45], v[114:115] neg_lo:[0,1] neg_hi:[0,1]
	v_pk_mul_f32 v[104:105], v[104:105], v[176:177]
	v_pk_mul_f32 v[44:45], v[44:45], v[176:177]
	v_pk_fma_f32 v[104:105], v[68:69], v[104:105], v[70:71] op_sel_hi:[0,1,0]
	v_pk_fma_f32 v[44:45], v[64:65], v[44:45], v[66:67] op_sel_hi:[0,1,0]
	v_mov_b32_e32 v114, v182
	v_mov_b32_e32 v115, v180
	v_pk_add_f32 v[100:101], v[100:101], v[114:115] neg_lo:[0,1] neg_hi:[0,1]
	v_mov_b32_e32 v180, v183
	v_pk_add_f32 v[34:35], v[34:35], v[114:115] neg_lo:[0,1] neg_hi:[0,1]
	v_pk_mul_f32 v[100:101], v[100:101], v[180:181]
	v_pk_mul_f32 v[34:35], v[34:35], v[180:181]
	v_pk_fma_f32 v[100:101], v[68:69], v[100:101], v[70:71] op_sel_hi:[0,1,0]
	v_pk_fma_f32 v[34:35], v[64:65], v[34:35], v[66:67] op_sel_hi:[0,1,0]
	v_mov_b32_e32 v114, v186
	v_mov_b32_e32 v115, v184
	v_pk_add_f32 v[98:99], v[98:99], v[114:115] neg_lo:[0,1] neg_hi:[0,1]
	v_mov_b32_e32 v184, v187
	v_pk_add_f32 v[40:41], v[40:41], v[114:115] neg_lo:[0,1] neg_hi:[0,1]
	v_pk_mul_f32 v[98:99], v[98:99], v[184:185]
	v_pk_mul_f32 v[40:41], v[40:41], v[184:185]
	v_pk_fma_f32 v[98:99], v[68:69], v[98:99], v[70:71] op_sel_hi:[0,1,0]
	v_pk_fma_f32 v[40:41], v[64:65], v[40:41], v[66:67] op_sel_hi:[0,1,0]
	v_mov_b32_e32 v114, v190
	v_mov_b32_e32 v115, v188
	v_pk_add_f32 v[94:95], v[94:95], v[114:115] neg_lo:[0,1] neg_hi:[0,1]
	v_mov_b32_e32 v188, v191
	v_pk_add_f32 v[32:33], v[32:33], v[114:115] neg_lo:[0,1] neg_hi:[0,1]
	v_pk_mul_f32 v[94:95], v[94:95], v[188:189]
	v_pk_mul_f32 v[32:33], v[32:33], v[188:189]
	v_pk_fma_f32 v[94:95], v[68:69], v[94:95], v[70:71] op_sel_hi:[0,1,0]
	v_pk_fma_f32 v[32:33], v[64:65], v[32:33], v[66:67] op_sel_hi:[0,1,0]
	v_mov_b32_e32 v114, v194
	v_mov_b32_e32 v115, v192
	v_pk_add_f32 v[76:77], v[76:77], v[114:115] neg_lo:[0,1] neg_hi:[0,1]
	v_mov_b32_e32 v192, v195
	v_pk_add_f32 v[36:37], v[36:37], v[114:115] neg_lo:[0,1] neg_hi:[0,1]
	v_pk_mul_f32 v[76:77], v[76:77], v[192:193]
	v_pk_mul_f32 v[36:37], v[36:37], v[192:193]
	v_pk_fma_f32 v[76:77], v[68:69], v[76:77], v[70:71] op_sel_hi:[0,1,0]
	v_pk_fma_f32 v[36:37], v[64:65], v[36:37], v[66:67] op_sel_hi:[0,1,0]
	v_mov_b32_e32 v78, v198
	v_mov_b32_e32 v79, v196
	v_pk_add_f32 v[74:75], v[74:75], v[78:79] neg_lo:[0,1] neg_hi:[0,1]
	v_mov_b32_e32 v196, v199
	v_pk_mul_f32 v[74:75], v[74:75], v[196:197]
	s_nop 0
	v_pk_fma_f32 v[74:75], v[68:69], v[74:75], v[70:71] op_sel_hi:[0,1,0]
	v_pk_add_f32 v[68:69], v[106:107], v[78:79] neg_lo:[0,1] neg_hi:[0,1]
	s_nop 0
	v_pk_mul_f32 v[68:69], v[68:69], v[196:197]
	s_nop 0
	v_pk_fma_f32 v[106:107], v[64:65], v[68:69], v[66:67] op_sel_hi:[0,1,0]
	s_branch .LBB0_230
